# attention unit prologue: tile-1 K/V loads issued with the tile-0 and Q loads (hidden under first LDS stage + QK MFMAs)
# speedup vs baseline: 1.0015x; 1.0015x over previous
.LBB0_1764:
	s_bitcmp0_b32 s52, 0
	s_cselect_b32 s39, s8, s40
	s_add_i32 s39, s39, s4
	s_cmpk_gt_i32 s39, 0x7ff
	s_cbranch_scc1 .LBB0_1763
	s_lshl_b32 s4, s39, 10
	s_and_b32 s4, s4, 0x6000
	s_ashr_i32 s53, s39, 5
	v_mov_b64_e32 v[16:17], s[6:7]
	s_lshl_b32 s36, s39, 7
	v_add_u32_e32 v0, s4, v166
	s_sub_i32 s38, 63, s53
	s_and_b32 s57, s36, 0x380
	v_mad_i64_i32 v[0:1], s[36:37], v0, s44, v[16:17]
	v_add_u32_e32 v2, s4, v168
	s_lshl_b32 s56, s38, 7
	s_lshl_b32 s36, s57, 1
	s_mov_b32 s37, s5
	v_mad_i64_i32 v[2:3], s[54:55], v2, s44, v[16:17]
	v_lshl_add_u64 v[0:1], v[0:1], 0, s[36:37]
	v_lshl_add_u64 v[2:3], v[2:3], 0, s[36:37]
	v_mov_b32_e32 v177, v163
	s_add_i32 s37, s56, s41
	v_lshl_add_u64 v[42:43], v[2:3], 0, v[176:177]
	s_add_i32 s37, s37, s4
	v_add_co_u32_e32 v12, vcc, s46, v42
	v_or_b32_e32 v178, s37, v160
	s_or_b32 s4, s57, s42
	v_lshl_add_u64 v[40:41], v[0:1], 0, v[162:163]
	v_addc_co_u32_e32 v13, vcc, 0, v43, vcc
	v_mad_u64_u32 v[16:17], s[54:55], v178, s44, v[16:17]
	s_lshl_b32 s4, s4, 1
	global_load_dwordx4 v[0:3], v[40:41], off
	global_load_dwordx4 v[4:7], v[40:41], off offset:128
	global_load_dwordx4 v[8:11], v[42:43], off offset:2048
	s_nop 0
	global_load_dwordx4 v[12:15], v[12:13], off offset:2048
	v_lshl_add_u64 v[16:17], v[16:17], 0, s[4:5]
	v_lshl_add_u64 v[16:17], v[164:165], 1, v[16:17]
	v_add_co_u32_e32 v18, vcc, s45, v16
	v_add_u32_e32 v177, s43, v186
	s_nop 0
	v_addc_co_u32_e32 v19, vcc, 0, v17, vcc
	global_load_dwordx4 v[144:147], v[18:19], off
	v_lshl_add_u64 v[16:17], v[16:17], 0, s[30:31]
	global_load_dwordx4 v[148:151], v[16:17], off offset:32
	global_load_dwordx4 v[152:155], v[16:17], off offset:64
	global_load_dwordx4 v[140:143], v[16:17], off offset:96
	v_add_u32_e32 v54, 0, v182
	v_add_u32_e32 v200, s43, v187
	v_add_u32_e32 v201, s43, v188
	v_add_u32_e32 v180, s43, v189
	v_add_co_u32_e32 v40, vcc, s47, v40
	v_mov_b32_e32 v53, v163
	s_nop 0
	v_addc_co_u32_e32 v41, vcc, 0, v41, vcc
	v_add_co_u32_e32 v48, vcc, s47, v42
	s_mov_b32 s4, 0
	s_nop 0
	v_addc_co_u32_e32 v49, vcc, 0, v43, vcc
	v_add_co_u32_e32 v50, vcc, s48, v42
	s_cmp_eq_u32 s53, 63
	s_nop 0
	v_addc_co_u32_e32 v51, vcc, 0, v43, vcc
	s_nop 0
	global_load_dwordx4 v[236:239], v[40:41], off
	global_load_dwordx4 v[240:243], v[40:41], off offset:128
	global_load_dwordx4 v[244:247], v[48:49], off offset:2048
	global_load_dwordx4 v[248:251], v[50:51], off offset:2048
	s_waitcnt vmcnt(11)
	ds_write_b128 v183, v[0:3]
	s_waitcnt vmcnt(10)
	ds_write_b128 v183, v[4:7] offset:8192
	s_waitcnt vmcnt(9)
	ds_write_b128 v54, v[8:11] offset:32768
	s_waitcnt vmcnt(8)
	ds_write_b128 v54, v[12:15] offset:40960
	s_waitcnt vmcnt(4) lgkmcnt(0)
	s_barrier
	ds_read_b128 v[0:3], v177
	ds_read_b128 v[4:7], v177 offset:4096
	s_waitcnt lgkmcnt(1)
	v_mfma_f32_32x32x16_bf16 v[16:31], v[0:3], v[144:147], 0
	ds_read_b128 v[32:35], v200
	ds_read_b128 v[36:39], v200 offset:4096
	s_waitcnt lgkmcnt(1)
	v_mfma_f32_32x32x16_bf16 v[16:31], v[32:35], v[148:151], v[16:31]
	ds_read_b128 v[32:35], v201
	v_mfma_f32_32x32x16_bf16 v[0:15], v[4:7], v[144:147], 0
	s_waitcnt lgkmcnt(1)
	v_mfma_f32_32x32x16_bf16 v[0:15], v[36:39], v[148:151], v[0:15]
	ds_read_b128 v[36:39], v201 offset:4096
	s_waitcnt lgkmcnt(1)
	v_mfma_f32_32x32x16_bf16 v[16:31], v[32:35], v[152:155], v[16:31]
	ds_read_b128 v[32:35], v180
	s_waitcnt lgkmcnt(1)
	v_mfma_f32_32x32x16_bf16 v[0:15], v[36:39], v[152:155], v[0:15]
	ds_read_b128 v[44:47], v180 offset:4096
	s_waitcnt lgkmcnt(1)
	v_mfma_f32_32x32x16_bf16 v[16:31], v[32:35], v[140:143], v[16:31]
	s_waitcnt vmcnt(3)
	ds_write_b128 v183, v[236:239] offset:16384
	s_waitcnt vmcnt(2)
	ds_write_b128 v183, v[240:243] offset:24576
	s_waitcnt vmcnt(1)
	ds_write_b128 v54, v[244:247] offset:49152
	s_waitcnt vmcnt(0)
	ds_write_b128 v54, v[248:251] offset:57344
	s_waitcnt lgkmcnt(4)
	v_mfma_f32_32x32x16_bf16 v[0:15], v[44:47], v[140:143], v[0:15]
	v_exp_f32_e32 v44, v16
	v_exp_f32_e32 v45, v17
	v_exp_f32_e32 v16, v18
	v_exp_f32_e32 v52, v19
	v_exp_f32_e32 v46, v20
	v_add_f32_e32 v17, v44, v45
	v_exp_f32_e32 v21, v21
	v_cvt_pk_bf16_f32 v157, v16, v52
	v_pk_add_f32 v[16:17], v[16:17], v[52:53]
	v_exp_f32_e32 v18, v22
	v_pk_add_f32 v[16:17], v[16:17], v[16:17] op_sel_hi:[0,1]
	v_exp_f32_e32 v24, v24
	v_exp_f32_e32 v25, v25
	v_exp_f32_e32 v16, v23
	v_add_f32_e32 v19, v46, v21
	v_cvt_pk_bf16_f32 v158, v46, v21
	v_add_f32_e32 v21, v24, v25
	v_cvt_pk_bf16_f32 v136, v24, v25
	v_pk_add_f32 v[24:25], v[18:19], v[16:17]
	v_exp_f32_e32 v20, v26
	v_pk_add_f32 v[24:25], v[24:25], v[24:25] op_sel_hi:[0,1]
	v_exp_f32_e32 v26, v28
	v_exp_f32_e32 v28, v29
	v_exp_f32_e32 v24, v27
	v_exp_f32_e32 v22, v30
	v_exp_f32_e32 v29, v0
	v_add_f32_e32 v23, v26, v28
	v_cvt_pk_bf16_f32 v138, v26, v28
	v_pk_add_f32 v[26:27], v[20:21], v[24:25]
	v_exp_f32_e32 v30, v1
	v_pk_add_f32 v[26:27], v[26:27], v[26:27] op_sel_hi:[0,1]
	v_exp_f32_e32 v26, v31
	v_exp_f32_e32 v0, v3
	v_add_f32_e32 v1, v29, v30
	v_cvt_pk_bf16_f32 v132, v29, v30
	v_pk_add_f32 v[28:29], v[22:23], v[26:27]
	v_exp_f32_e32 v3, v4
	v_pk_add_f32 v[28:29], v[28:29], v[28:29] op_sel_hi:[0,1]
	v_exp_f32_e32 v47, v5
	v_exp_f32_e32 v28, v2
	v_exp_f32_e32 v4, v6
	v_exp_f32_e32 v6, v8
	v_add_f32_e32 v5, v3, v47
	v_cvt_pk_bf16_f32 v134, v3, v47
	v_pk_add_f32 v[2:3], v[28:29], v[0:1]
	v_cvt_pk_bf16_f32 v133, v28, v0
	v_pk_add_f32 v[2:3], v[2:3], v[2:3] op_sel_hi:[0,1]
	v_exp_f32_e32 v2, v7
	v_exp_f32_e32 v55, v9
	v_exp_f32_e32 v8, v10
	v_exp_f32_e32 v10, v12
	v_pk_add_f32 v[0:1], v[4:5], v[2:3]
	v_add_f32_e32 v9, v6, v55
	v_pk_add_f32 v[0:1], v[0:1], v[0:1] op_sel_hi:[0,1]
	v_exp_f32_e32 v0, v11
	v_cvt_pk_bf16_f32 v135, v4, v2
	v_exp_f32_e32 v56, v13
	v_exp_f32_e32 v12, v14
	v_pk_add_f32 v[2:3], v[8:9], v[0:1]
	v_cvt_pk_bf16_f32 v129, v8, v0
	v_pk_add_f32 v[2:3], v[2:3], v[2:3] op_sel_hi:[0,1]
	v_exp_f32_e32 v2, v15
	v_add_f32_e32 v13, v10, v56
	v_cvt_pk_bf16_f32 v156, v44, v45
	v_cvt_pk_bf16_f32 v128, v6, v55
	v_pk_add_f32 v[0:1], v[12:13], v[2:3]
	v_cvt_pk_bf16_f32 v130, v10, v56
	v_cvt_pk_bf16_f32 v159, v18, v16
	v_cvt_pk_bf16_f32 v137, v20, v24
	v_cvt_pk_bf16_f32 v139, v22, v26
	v_cvt_pk_bf16_f32 v131, v12, v2
	v_add_f32_e32 v181, v0, v1
	s_waitcnt lgkmcnt(0)
	s_barrier
	s_cbranch_scc1 .LBB0_1769
	s_bfe_u32 s37, s39, 0x20003
	s_and_b32 s4, s39, 7
	v_mad_u64_u32 v[96:97], s[54:55], s37, v199, v[172:173]
	v_mad_u64_u32 v[98:99], s[54:55], s37, v199, v[174:175]
	v_mov_b32_e32 v0, 0
	s_mov_b32 s53, 1
	s_lshl_b32 s38, s38, 1
	s_lshl_b32 s4, s4, 8
	s_mov_b32 s54, 0
	s_movk_i32 s39, 0x4000
	v_mov_b32_e32 v1, v0
	v_mov_b32_e32 v2, v0
	v_mov_b32_e32 v3, v0
	v_mov_b32_e32 v4, v0
	v_mov_b32_e32 v5, v0
	v_mov_b32_e32 v6, v0
	v_mov_b32_e32 v7, v0
	v_mov_b32_e32 v8, v0
	v_mov_b32_e32 v9, v0
	v_mov_b32_e32 v10, v0
	v_mov_b32_e32 v11, v0
	v_mov_b32_e32 v12, v0
	v_mov_b32_e32 v13, v0
	v_mov_b32_e32 v14, v0
	v_mov_b32_e32 v15, v0
	v_mov_b32_e32 v48, v0
	v_mov_b32_e32 v49, v0
	v_mov_b32_e32 v50, v0
	v_mov_b32_e32 v51, v0
	v_mov_b32_e32 v52, v0
	v_mov_b32_e32 v53, v0
	v_mov_b32_e32 v54, v0
	v_mov_b32_e32 v55, v0
	v_mov_b32_e32 v56, v0
	v_mov_b32_e32 v57, v0
	v_mov_b32_e32 v58, v0
	v_mov_b32_e32 v59, v0
	v_mov_b32_e32 v60, v0
	v_mov_b32_e32 v61, v0
	v_mov_b32_e32 v62, v0
	v_mov_b32_e32 v63, v0
	v_mov_b32_e32 v32, v0
	v_mov_b32_e32 v33, v0
	v_mov_b32_e32 v34, v0
	v_mov_b32_e32 v35, v0
	v_mov_b32_e32 v36, v0
	v_mov_b32_e32 v37, v0
	v_mov_b32_e32 v38, v0
	v_mov_b32_e32 v39, v0
	v_mov_b32_e32 v40, v0
	v_mov_b32_e32 v41, v0
	v_mov_b32_e32 v42, v0
	v_mov_b32_e32 v43, v0
	v_mov_b32_e32 v44, v0
	v_mov_b32_e32 v45, v0
	v_mov_b32_e32 v46, v0
	v_mov_b32_e32 v47, v0
	v_mov_b32_e32 v16, v0
	v_mov_b32_e32 v17, v0
	v_mov_b32_e32 v18, v0
	v_mov_b32_e32 v19, v0
	v_mov_b32_e32 v20, v0
	v_mov_b32_e32 v21, v0
	v_mov_b32_e32 v22, v0
	v_mov_b32_e32 v23, v0
	v_mov_b32_e32 v24, v0
	v_mov_b32_e32 v25, v0
	v_mov_b32_e32 v26, v0
	v_mov_b32_e32 v27, v0
	v_mov_b32_e32 v28, v0
	v_mov_b32_e32 v29, v0
	v_mov_b32_e32 v30, v0
	v_mov_b32_e32 v31, v0
